# NSA streaming loop: hand-written fast path (all K/V fragment ds_reads up front, in-place accumulation) plus LDS chunk swizzle for conflict-free ds_read_b128
# speedup vs baseline: 1.0202x; 1.0094x over previous
.LBB0_581:
	s_or_b64 exec, exec, s[2:3]
	s_lshl_b32 s0, s15, 3
	v_readlane_b32 s1, v254, 9
	v_mul_f32_e32 v32, 0xbfb8aa3b, v72
	s_add_i32 s0, s1, s0
	v_and_b32_e32 v33, 31, v75
	v_exp_f32_e32 v34, v32
	v_lshl_add_u32 v32, v88, 3, s0
	v_lshl_add_u32 v33, v33, 3, s1
	s_waitcnt lgkmcnt(0)
	s_barrier
	ds_read_b64 v[60:61], v32
	ds_read_b64 v[32:33], v33
	v_mul_f32_e32 v35, 0xbfb8aa3b, v74
	v_exp_f32_e32 v35, v35
	v_lshlrev_b64 v[68:69], 16, v[82:83]
	v_add_f32_e32 v34, 1.0, v34
	s_waitcnt lgkmcnt(0)
	ds_bpermute_b32 v40, v108, v33
	ds_bpermute_b32 v41, v108, v32
	v_add_f32_e32 v35, 1.0, v35
	v_rcp_f32_e32 v83, v35
	v_xor_b32_e32 v35, 8, v174
	v_cmp_lt_i32_e32 vcc, v35, v116
	s_waitcnt lgkmcnt(1)
	v_or_b32_e32 v33, v40, v33
	s_waitcnt lgkmcnt(0)
	v_or_b32_e32 v32, v41, v32
	v_cndmask_b32_e32 v35, v174, v35, vcc
	v_lshlrev_b32_e32 v35, 2, v35
	ds_bpermute_b32 v40, v35, v33
	ds_bpermute_b32 v35, v35, v32
	v_rcp_f32_e32 v34, v34
	s_lshr_b32 s55, s14, 6
	s_lshl_b64 s[0:1], 2, s55
	s_add_u32 s0, s0, -1
	s_waitcnt lgkmcnt(0)
	v_pk_fma_f32 v[74:75], v[34:35], v[28:29], 0 op_sel_hi:[0,1,0]
	v_xor_b32_e32 v28, 4, v174
	v_cmp_lt_i32_e32 vcc, v28, v116
	v_pk_fma_f32 v[58:59], v[34:35], v[26:27], 0 op_sel_hi:[0,1,0]
	v_or_b32_e32 v26, v40, v33
	v_cndmask_b32_e32 v28, v174, v28, vcc
	v_or_b32_e32 v27, v35, v32
	v_lshlrev_b32_e32 v28, 2, v28
	ds_bpermute_b32 v29, v28, v26
	ds_bpermute_b32 v28, v28, v27
	v_pk_fma_f32 v[64:65], v[34:35], v[20:21], 0 op_sel_hi:[0,1,0]
	v_pk_fma_f32 v[62:63], v[34:35], v[22:23], 0 op_sel_hi:[0,1,0]
	s_addc_u32 s1, s1, -1
	s_waitcnt lgkmcnt(1)
	v_or_b32_e32 v20, v29, v26
	s_waitcnt lgkmcnt(0)
	v_or_b32_e32 v21, v28, v27
	ds_bpermute_b32 v22, v37, v20
	ds_bpermute_b32 v23, v37, v21
	s_cmp_lg_u32 s55, 63
	v_pk_fma_f32 v[56:57], v[34:35], v[18:19], 0 op_sel_hi:[0,1,0]
	v_mul_f32_e32 v18, 0xbfb8aa3b, v73
	s_cselect_b32 s1, s1, -1
	s_cselect_b32 s0, s0, -1
	s_lshl_b32 s2, s10, 1
	v_exp_f32_e32 v18, v18
	s_waitcnt lgkmcnt(1)
	v_or_b32_e32 v19, v22, v20
	s_waitcnt lgkmcnt(0)
	v_or_b32_e32 v20, v23, v21
	s_add_u32 s58, s92, s2
	ds_bpermute_b32 v21, v36, v19
	ds_bpermute_b32 v22, v36, v20
	s_addc_u32 s59, s93, 0
	v_readlane_b32 s2, v253, 61
	v_readlane_b32 s3, v253, 62
	s_add_u32 s60, s2, s11
	v_readlane_b32 s2, v254, 32
	s_addc_u32 s61, s3, 0
	s_sub_i32 s2, 0xde0, s2
	v_pk_fma_f32 v[70:71], v[34:35], v[16:17], 0 op_sel_hi:[0,1,0]
	v_add_f32_e32 v16, 1.0, v18
	s_ashr_i32 s2, s2, 6
	v_mul_u32_u24_e32 v113, 0x90, v114
	v_rcp_f32_e32 v114, v16
	s_cmpk_gt_i32 s14, 0x1fe
	s_waitcnt lgkmcnt(1)
	v_or_b32_e32 v16, v21, v19
	s_waitcnt lgkmcnt(0)
	v_or_b32_e32 v17, v22, v20
	s_cselect_b32 s2, s2, 0
	v_and_b32_e32 v16, s1, v16
	v_and_b32_e32 v17, s0, v17
	s_lshl_b64 s[2:3], -1, s2
	v_add3_u32 v116, 0, v89, v76
	v_mul_u32_u24_e32 v110, 0x90, v110
	v_mul_u32_u24_e32 v111, 0x90, v111
	v_mul_u32_u24_e32 v112, 0x90, v112
	v_pk_fma_f32 v[66:67], v[34:35], v[30:31], 0 op_sel_hi:[0,1,0]
	v_pk_fma_f32 v[86:87], v[34:35], v[24:25], 0 op_sel_hi:[0,1,0]
	v_readfirstlane_b32 s56, v16
	v_readfirstlane_b32 s57, v17
	s_and_b64 s[34:35], s[0:1], s[2:3]
	v_lshl_add_u32 v117, v90, 1, v116
	s_add_i32 s62, s54, 0xfffffe03
	v_add_u32_e32 v118, 0xfffffe00, v78
	v_mul_u32_u24_e32 v119, 0x90, v38
	v_mul_u32_u24_e32 v120, 0x90, v39
	v_and_b32_e32 v211, 1, v210
	v_lshlrev_b32_e32 v211, 5, v211
	v_sub_u32_e32 v211, 16, v211
	v_lshrrev_b32_e32 v228, 1, v82
	v_xor_b32_e32 v228, v228, v82
	v_bfe_u32 v229, v228, 3, 1
	v_bfe_u32 v228, v228, 2, 1
	v_mad_i32_i24 v117, v229, v211, v117
	v_mad_i32_i24 v116, v228, v211, v116
	v_lshrrev_b32_e32 v228, 1, v210
	v_xor_b32_e32 v228, v228, v210
	v_bfe_u32 v228, v228, 2, 1
	v_lshlrev_b32_e32 v228, 4, v228
	v_xor_b32_e32 v208, v103, v228
	v_xor_b32_e32 v209, v115, v228
	s_mov_b64 s[36:37], 0
	s_mov_b64 s[38:39], -1
	s_branch .LBB0_583

.LBB0_602:
	s_mov_b32 s0, 0xffff
	v_cmp_ne_u32_e32 vcc, s0, v127
	s_and_b64 s[0:1], s[6:7], vcc
	v_cndmask_b32_e64 v40, 0, 1, s[0:1]
	s_mul_i32 s0, s63, 0x2500
	s_add_i32 s0, s0, 0
	v_cmp_ne_u32_e32 vcc, 0, v40
	v_add_u32_e32 v40, s0, v110
	v_add_u32_e32 v41, s0, v111
	v_add_u32_e32 v42, s0, v112
	v_add_u32_e32 v43, s0, v113
	s_mul_i32 s0, s63, 0x2400
	v_add3_u32 v126, v40, v79, v208
	v_add3_u32 v125, v41, v79, v208
	v_add3_u32 v124, v42, v104, v208
	v_add3_u32 v90, v43, v104, v208
	v_add_u32_e32 v123, s0, v209
	s_cbranch_vccz .Lnsa_fast
	ds_read_b128 v[40:43], v126
	ds_read_b128 v[44:47], v126 offset:64
	v_add_u32_e32 v146, v123, v120
	s_waitcnt lgkmcnt(1)
	v_mfma_f32_16x16x32_bf16 v[40:43], v[40:43], v[4:7], 0
	ds_read_b128 v[128:131], v90 offset:64
	s_waitcnt lgkmcnt(1)
	v_mfma_f32_16x16x32_bf16 v[52:55], v[44:47], v[0:3], v[40:43]
	ds_read_b128 v[44:47], v125 offset:64
	s_nop 3
	ds_read_b128 v[40:43], v125
	s_waitcnt lgkmcnt(0)
	v_mfma_f32_16x16x32_bf16 v[40:43], v[40:43], v[4:7], 0
	v_mfma_f32_16x16x32_bf16 v[48:51], v[44:47], v[0:3], v[40:43]
	ds_read_b128 v[44:47], v124 offset:64
	s_nop 5
	ds_read_b128 v[40:43], v124
	s_waitcnt lgkmcnt(0)
	v_mfma_f32_16x16x32_bf16 v[40:43], v[40:43], v[4:7], 0
	v_mfma_f32_16x16x32_bf16 v[44:47], v[44:47], v[0:3], v[40:43]
	s_nop 6
	ds_read_b128 v[40:43], v90
	s_waitcnt lgkmcnt(0)
	v_mfma_f32_16x16x32_bf16 v[40:43], v[40:43], v[4:7], 0
	v_mfma_f32_16x16x32_bf16 v[40:43], v[128:131], v[0:3], v[40:43]
	v_and_b32_e32 v128, 1, v127
	v_cmp_eq_u32_e32 vcc, 0, v128
	v_max_f32_e32 v128, v52, v52
	v_max_f32_e32 v128, 0xf149f2ca, v128
	v_and_b32_e32 v129, 2, v127
	v_cndmask_b32_e32 v128, v128, v92, vcc
	v_cmp_eq_u32_e64 s[10:11], 0, v129
	v_max_f32_e32 v129, v53, v53
	v_max_f32_e32 v129, v128, v129
	v_cndmask_b32_e64 v128, v129, v128, s[10:11]
	v_and_b32_e32 v129, 4, v127
	v_cmp_eq_u32_e64 s[26:27], 0, v129
	v_max_f32_e32 v129, v54, v54
	v_max_f32_e32 v129, v128, v129
	v_cndmask_b32_e64 v128, v129, v128, s[26:27]
	v_and_b32_e32 v129, 8, v127
	v_cmp_eq_u32_e64 s[30:31], 0, v129
	v_max_f32_e32 v129, v55, v55
	v_max_f32_e32 v129, v128, v129
	v_cndmask_b32_e64 v128, v129, v128, s[30:31]
	v_and_b32_e32 v129, 16, v127
	v_cmp_eq_u32_e64 s[24:25], 0, v129
	v_max_f32_e32 v129, v48, v48
	v_max_f32_e32 v129, v128, v129
	v_cndmask_b32_e64 v128, v129, v128, s[24:25]
	v_and_b32_e32 v129, 32, v127
	v_cmp_eq_u32_e64 s[28:29], 0, v129
	v_max_f32_e32 v129, v128, v128
	v_max_f32_e32 v130, v49, v49
	v_max_f32_e32 v129, v129, v130
	v_cndmask_b32_e64 v128, v129, v128, s[28:29]
	v_and_b32_e32 v129, 64, v127
	v_cmp_eq_u32_e64 s[18:19], 0, v129
	v_max_f32_e32 v129, v128, v128
	v_max_f32_e32 v130, v50, v50
	v_max_f32_e32 v129, v129, v130
	v_cndmask_b32_e64 v128, v129, v128, s[18:19]
	v_and_b32_e32 v129, 0x80, v127
	v_cmp_eq_u32_e64 s[20:21], 0, v129
	v_max_f32_e32 v129, v128, v128
	v_max_f32_e32 v130, v51, v51
	v_max_f32_e32 v129, v129, v130
	v_cndmask_b32_e64 v128, v129, v128, s[20:21]
	v_and_b32_e32 v129, 0x100, v127
	v_cmp_eq_u32_e64 s[22:23], 0, v129
	v_max_f32_e32 v129, v128, v128
	v_max_f32_e32 v130, v44, v44
	v_max_f32_e32 v129, v129, v130
	v_cndmask_b32_e64 v128, v129, v128, s[22:23]
	v_and_b32_e32 v129, 0x200, v127
	v_cmp_eq_u32_e64 s[8:9], 0, v129
	v_max_f32_e32 v129, v128, v128
	v_max_f32_e32 v130, v45, v45
	v_max_f32_e32 v129, v129, v130
	v_cndmask_b32_e64 v128, v129, v128, s[8:9]
	v_and_b32_e32 v129, 0x400, v127
	v_cmp_eq_u32_e64 s[12:13], 0, v129
	v_max_f32_e32 v129, v128, v128
	v_max_f32_e32 v130, v46, v46
	v_max_f32_e32 v129, v129, v130
	v_cndmask_b32_e64 v128, v129, v128, s[12:13]
	v_and_b32_e32 v129, 0x800, v127
	v_cmp_eq_u32_e64 s[14:15], 0, v129
	v_max_f32_e32 v129, v128, v128
	v_max_f32_e32 v130, v47, v47
	v_max_f32_e32 v129, v129, v130
	v_cndmask_b32_e64 v128, v129, v128, s[14:15]
	v_and_b32_e32 v129, 0x1000, v127
	v_cmp_eq_u32_e64 s[16:17], 0, v129
	v_max_f32_e32 v129, v128, v128
	v_max_f32_e32 v130, v40, v40
	v_max_f32_e32 v129, v129, v130
	v_cndmask_b32_e64 v128, v129, v128, s[16:17]
	v_and_b32_e32 v129, 0x2000, v127
	v_cmp_eq_u32_e64 s[0:1], 0, v129
	v_max_f32_e32 v129, v128, v128
	v_max_f32_e32 v130, v41, v41
	v_max_f32_e32 v129, v129, v130
	v_cndmask_b32_e64 v128, v129, v128, s[0:1]
	v_and_b32_e32 v129, 0x4000, v127
	v_cmp_eq_u32_e64 s[2:3], 0, v129
	v_max_f32_e32 v129, v128, v128
	v_max_f32_e32 v130, v42, v42
	v_max_f32_e32 v129, v129, v130
	v_cndmask_b32_e64 v128, v129, v128, s[2:3]
	v_and_b32_e32 v127, 0x8000, v127
	v_cmp_eq_u32_e64 s[4:5], 0, v127
	v_max_f32_e32 v127, v128, v128
	v_max_f32_e32 v129, v43, v43
	v_max_f32_e32 v127, v127, v129
	v_cndmask_b32_e64 v127, v127, v128, s[4:5]
	v_mov_b32_e32 v128, v127
	s_nop 1
	v_permlane16_swap_b32_e32 v128, v127
	v_max_f32_e32 v127, v127, v128
	v_mov_b32_e32 v128, v127
	s_nop 1
	v_permlane32_swap_b32_e32 v128, v127
	v_max3_f32 v127, v122, v127, v128
	v_sub_f32_e32 v53, v53, v127
	v_exp_f32_e32 v53, v53
	v_sub_f32_e32 v49, v49, v127
	v_exp_f32_e32 v49, v49
	v_sub_f32_e32 v52, v52, v127
	v_cndmask_b32_e64 v131, v53, 0, s[10:11]
	v_sub_f32_e32 v53, v54, v127
	v_exp_f32_e32 v53, v53
	v_exp_f32_e32 v52, v52
	v_sub_f32_e32 v45, v45, v127
	v_cndmask_b32_e64 v135, v49, 0, s[28:29]
	v_sub_f32_e32 v49, v50, v127
	v_exp_f32_e32 v45, v45
	v_cndmask_b32_e64 v132, v53, 0, s[26:27]
	v_sub_f32_e32 v53, v55, v127
	v_exp_f32_e32 v49, v49
	v_exp_f32_e32 v53, v53
	v_sub_f32_e32 v48, v48, v127
	v_cndmask_b32_e64 v130, v52, 0, vcc
	v_exp_f32_e32 v48, v48
	v_sub_f32_e32 v41, v41, v127
	v_add_f32_e32 v52, 0, v130
	v_cndmask_b32_e64 v139, v45, 0, s[8:9]
	v_sub_f32_e32 v45, v46, v127
	v_exp_f32_e32 v41, v41
	v_add_f32_e32 v52, v131, v52
	v_cndmask_b32_e64 v136, v49, 0, s[18:19]
	v_sub_f32_e32 v49, v51, v127
	v_exp_f32_e32 v45, v45
	v_add_f32_e32 v52, v132, v52
	v_cndmask_b32_e64 v133, v53, 0, s[30:31]
	v_exp_f32_e32 v49, v49
	v_sub_f32_e32 v44, v44, v127
	v_add_f32_e32 v52, v133, v52
	v_cndmask_b32_e64 v134, v48, 0, s[24:25]
	v_exp_f32_e32 v44, v44
	v_add_f32_e32 v48, v134, v52
	v_cndmask_b32_e64 v143, v41, 0, s[0:1]
	v_sub_f32_e32 v41, v42, v127
	v_sub_f32_e32 v129, v122, v127
	v_add_f32_e32 v48, v135, v48
	v_cndmask_b32_e64 v140, v45, 0, s[12:13]
	v_sub_f32_e32 v45, v47, v127
	v_exp_f32_e32 v41, v41
	v_add_f32_e32 v48, v136, v48
	v_cndmask_b32_e64 v137, v49, 0, s[20:21]
	v_exp_f32_e32 v45, v45
	v_sub_f32_e32 v40, v40, v127
	v_exp_f32_e32 v52, v129
	v_add_u32_e32 v129, v123, v119
	v_add_f32_e32 v48, v137, v48
	v_cndmask_b32_e64 v138, v44, 0, s[22:23]
	v_exp_f32_e32 v40, v40
	v_cvt_pk_bf16_f32 v130, v130, v131
	v_cvt_pk_bf16_f32 v131, v132, v133
	v_cvt_pk_bf16_f32 v132, v134, v135
	v_cvt_pk_bf16_f32 v133, v136, v137
	ds_read_b128 v[134:137], v129 offset:38912
	v_add_f32_e32 v44, v138, v48
	v_add_f32_e32 v44, v139, v44
	v_cndmask_b32_e64 v144, v41, 0, s[2:3]
	v_sub_f32_e32 v41, v43, v127
	v_add_f32_e32 v44, v140, v44
	v_cndmask_b32_e64 v141, v45, 0, s[14:15]
	v_exp_f32_e32 v41, v41
	v_add_f32_e32 v44, v141, v44
	v_cndmask_b32_e64 v142, v40, 0, s[16:17]
	v_add_f32_e32 v40, v142, v44
	v_add_f32_e32 v40, v143, v40
	v_add_f32_e32 v40, v144, v40
	v_cndmask_b32_e64 v145, v41, 0, s[4:5]
	v_add_f32_e32 v128, v145, v40
	v_pk_mul_f32 v[42:43], v[38:39], v[52:53] op_sel_hi:[1,0]
	v_pk_mul_f32 v[40:41], v[36:37], v[52:53] op_sel_hi:[1,0]
	v_pk_mul_f32 v[46:47], v[34:35], v[52:53] op_sel_hi:[1,0]
	v_pk_mul_f32 v[44:45], v[32:33], v[52:53] op_sel_hi:[1,0]
	s_waitcnt lgkmcnt(0)
	v_mfma_f32_16x16x32_bf16 v[40:43], v[134:137], v[130:133], v[40:43]
	ds_read_b128 v[134:137], v129 offset:41216
	v_pk_mul_f32 v[50:51], v[30:31], v[52:53] op_sel_hi:[1,0]
	v_pk_mul_f32 v[48:49], v[28:29], v[52:53] op_sel_hi:[1,0]
	s_waitcnt lgkmcnt(0)
	v_mfma_f32_16x16x32_bf16 v[44:47], v[134:137], v[130:133], v[44:47]
	ds_read_b128 v[134:137], v129 offset:43520
	v_fmac_f32_e32 v128, v121, v52
	v_pk_mul_f32 v[54:55], v[26:27], v[52:53] op_sel_hi:[1,0]
	s_waitcnt lgkmcnt(0)
	v_mfma_f32_16x16x32_bf16 v[48:51], v[134:137], v[130:133], v[48:51]
	ds_read_b128 v[134:137], v146 offset:38912
	v_pk_mul_f32 v[52:53], v[24:25], v[52:53] op_sel_hi:[1,0]
	s_waitcnt lgkmcnt(0)
	s_nop 0
	v_mfma_f32_16x16x32_bf16 v[52:55], v[134:137], v[130:133], v[52:55]
	v_cvt_pk_bf16_f32 v130, v138, v139
	v_cvt_pk_bf16_f32 v131, v140, v141
	v_cvt_pk_bf16_f32 v132, v142, v143
	v_cvt_pk_bf16_f32 v133, v144, v145
	ds_read_b128 v[134:137], v129 offset:38976
	s_waitcnt lgkmcnt(0)
	v_mfma_f32_16x16x32_bf16 v[40:43], v[134:137], v[130:133], v[40:43]
	ds_read_b128 v[134:137], v129 offset:41280
	s_waitcnt lgkmcnt(0)
	v_mfma_f32_16x16x32_bf16 v[44:47], v[134:137], v[130:133], v[44:47]
	ds_read_b128 v[134:137], v129 offset:43584
	s_waitcnt lgkmcnt(0)
	v_mfma_f32_16x16x32_bf16 v[48:51], v[134:137], v[130:133], v[48:51]
	ds_read_b128 v[134:137], v146 offset:38976
	s_waitcnt lgkmcnt(0)
	v_mfma_f32_16x16x32_bf16 v[52:55], v[134:137], v[130:133], v[52:55]
	s_branch .LBB0_608
.Lnsa_fast:
	ds_read_b128 v[176:179], v126
	ds_read_b128 v[180:183], v125
	ds_read_b128 v[184:187], v124
	ds_read_b128 v[188:191], v90
	ds_read_b128 v[192:195], v126 offset:64
	ds_read_b128 v[196:199], v125 offset:64
	ds_read_b128 v[200:203], v124 offset:64
	ds_read_b128 v[204:207], v90 offset:64
	v_add_u32_e32 v172, v123, v119
	v_add_u32_e32 v173, v123, v120
	v_cndmask_b32_e64 v168, v102, 0, s[6:7]
	v_mov_b32_e32 v169, v168
	v_mov_b32_e32 v170, v168
	v_mov_b32_e32 v171, v168
	ds_read_b128 v[212:215], v172 offset:38912
	ds_read_b128 v[216:219], v172 offset:41216
	ds_read_b128 v[220:223], v172 offset:43520
	ds_read_b128 v[224:227], v173 offset:38912
	ds_read_b128 v[232:235], v172 offset:38976
	ds_read_b128 v[236:239], v172 offset:41280
	s_waitcnt lgkmcnt(13)
	v_mfma_f32_16x16x32_bf16 v[52:55], v[176:179], v[4:7], v[168:171]
	ds_read_b128 v[240:243], v172 offset:43584
	s_waitcnt lgkmcnt(13)
	v_mfma_f32_16x16x32_bf16 v[48:51], v[180:183], v[4:7], v[168:171]
	ds_read_b128 v[244:247], v173 offset:38976
	s_waitcnt lgkmcnt(13)
	v_mfma_f32_16x16x32_bf16 v[44:47], v[184:187], v[4:7], v[168:171]
	s_waitcnt lgkmcnt(12)
	v_mfma_f32_16x16x32_bf16 v[40:43], v[188:191], v[4:7], v[168:171]
	s_waitcnt lgkmcnt(11)
	v_mfma_f32_16x16x32_bf16 v[52:55], v[192:195], v[0:3], v[52:55]
	s_waitcnt lgkmcnt(10)
	v_mfma_f32_16x16x32_bf16 v[48:51], v[196:199], v[0:3], v[48:51]
	s_waitcnt lgkmcnt(9)
	v_mfma_f32_16x16x32_bf16 v[44:47], v[200:203], v[0:3], v[44:47]
	s_waitcnt lgkmcnt(8)
	v_mfma_f32_16x16x32_bf16 v[40:43], v[204:207], v[0:3], v[40:43]
	s_nop 4
	v_max3_f32 v90, v52, v53, v54
	v_max3_f32 v90, v90, v55, v48
	v_max3_f32 v90, v90, v49, v50
	v_max3_f32 v90, v90, v51, v44
	v_max3_f32 v90, v90, v45, v46
	v_max3_f32 v90, v90, v47, v40
	v_max3_f32 v90, v90, v41, v42
	v_max_f32_e32 v90, v90, v43
	v_mov_b32_e32 v124, v90
	s_nop 1
	v_permlane16_swap_b32_e32 v124, v90
	v_max_f32_e32 v90, v90, v124
	v_mov_b32_e32 v124, v90
	s_nop 1
	v_permlane32_swap_b32_e32 v124, v90
	v_max3_f32 v127, v122, v90, v124
	v_sub_f32_e32 v90, v122, v127
	v_exp_f32_e32 v90, v90
	v_cmp_gt_f32_e32 vcc, v127, v122
	s_cbranch_vccz .Lnsa_fast_norescale
	v_pk_mul_f32 v[38:39], v[38:39], v[90:91] op_sel_hi:[1,0]
	v_pk_mul_f32 v[36:37], v[36:37], v[90:91] op_sel_hi:[1,0]
	v_pk_mul_f32 v[34:35], v[34:35], v[90:91] op_sel_hi:[1,0]
	v_pk_mul_f32 v[32:33], v[32:33], v[90:91] op_sel_hi:[1,0]
	v_pk_mul_f32 v[30:31], v[30:31], v[90:91] op_sel_hi:[1,0]
	v_pk_mul_f32 v[28:29], v[28:29], v[90:91] op_sel_hi:[1,0]
	v_pk_mul_f32 v[26:27], v[26:27], v[90:91] op_sel_hi:[1,0]
	v_pk_mul_f32 v[24:25], v[24:25], v[90:91] op_sel_hi:[1,0]
.Lnsa_fast_norescale:
	v_sub_f32_e32 v52, v52, v127
	v_sub_f32_e32 v53, v53, v127
	v_sub_f32_e32 v54, v54, v127
	v_sub_f32_e32 v55, v55, v127
	v_exp_f32_e32 v128, v52
	v_exp_f32_e32 v129, v53
	v_exp_f32_e32 v130, v54
	v_exp_f32_e32 v131, v55
	v_sub_f32_e32 v48, v48, v127
	v_sub_f32_e32 v49, v49, v127
	v_sub_f32_e32 v50, v50, v127
	v_sub_f32_e32 v51, v51, v127
	v_exp_f32_e32 v132, v48
	v_exp_f32_e32 v133, v49
	v_exp_f32_e32 v134, v50
	v_exp_f32_e32 v135, v51
	v_sub_f32_e32 v44, v44, v127
	v_sub_f32_e32 v45, v45, v127
	v_sub_f32_e32 v46, v46, v127
	v_sub_f32_e32 v47, v47, v127
	v_exp_f32_e32 v136, v44
	v_exp_f32_e32 v137, v45
	v_exp_f32_e32 v138, v46
	v_exp_f32_e32 v139, v47
	v_sub_f32_e32 v40, v40, v127
	v_sub_f32_e32 v41, v41, v127
	v_sub_f32_e32 v42, v42, v127
	v_sub_f32_e32 v43, v43, v127
	v_exp_f32_e32 v140, v40
	v_exp_f32_e32 v141, v41
	v_exp_f32_e32 v142, v42
	v_exp_f32_e32 v143, v43
	v_cvt_pk_bf16_f32 v248, v128, v129
	v_cvt_pk_bf16_f32 v249, v130, v131
	v_cvt_pk_bf16_f32 v250, v132, v133
	v_cvt_pk_bf16_f32 v251, v134, v135
	v_cvt_pk_bf16_f32 v52, v136, v137
	v_cvt_pk_bf16_f32 v53, v138, v139
	v_cvt_pk_bf16_f32 v54, v140, v141
	v_cvt_pk_bf16_f32 v55, v142, v143
	s_waitcnt lgkmcnt(7)
	v_mfma_f32_16x16x32_bf16 v[36:39], v[212:215], v[248:251], v[36:39]
	v_add_f32_e32 v40, v132, v128
	v_add_f32_e32 v41, v133, v129
	s_waitcnt lgkmcnt(6)
	v_mfma_f32_16x16x32_bf16 v[32:35], v[216:219], v[248:251], v[32:35]
	v_add_f32_e32 v42, v134, v130
	v_add_f32_e32 v43, v135, v131
	s_waitcnt lgkmcnt(5)
	v_mfma_f32_16x16x32_bf16 v[28:31], v[220:223], v[248:251], v[28:31]
	v_add_f32_e32 v40, v136, v40
	v_add_f32_e32 v41, v137, v41
	s_waitcnt lgkmcnt(4)
	v_mfma_f32_16x16x32_bf16 v[24:27], v[224:227], v[248:251], v[24:27]
	v_add_f32_e32 v42, v138, v42
	v_add_f32_e32 v43, v139, v43
	s_waitcnt lgkmcnt(3)
	v_mfma_f32_16x16x32_bf16 v[36:39], v[232:235], v[52:55], v[36:39]
	v_add_f32_e32 v40, v140, v40
	v_add_f32_e32 v41, v141, v41
	s_waitcnt lgkmcnt(2)
	v_mfma_f32_16x16x32_bf16 v[32:35], v[236:239], v[52:55], v[32:35]
	v_add_f32_e32 v42, v142, v42
	v_add_f32_e32 v43, v143, v43
	s_waitcnt lgkmcnt(1)
	v_mfma_f32_16x16x32_bf16 v[28:31], v[240:243], v[52:55], v[28:31]
	v_add_f32_e32 v40, v40, v41
	v_fmac_f32_e32 v40, v121, v90
	s_waitcnt lgkmcnt(0)
	v_mfma_f32_16x16x32_bf16 v[24:27], v[244:247], v[52:55], v[24:27]
	v_add_f32_e32 v42, v42, v43
	v_mov_b32_e32 v122, v127
	v_add_f32_e32 v121, v42, v40
	s_branch .Lnsa_fast_done

.Lnsa_fast_done:
	s_andn2_b64 vcc, exec, s[52:53]
	s_xor_b32 s63, s63, 1
	s_cbranch_vccz .LBB0_594
	s_branch .LBB0_595
